# MLA epilogue: neighbour-lane exchange by DPP quad_perm instead of 64 serialized ds_bpermute round trips per pass
# baseline (speedup 1.0000x reference)
.LBB0_528:
	s_or_b64 exec, exec, s[18:19]
	s_waitcnt lgkmcnt(0)
	v_add_u32_e32 v2, s23, v193
	v_and_b32_e32 v86, 64, v202
	ds_read_b128 v[82:85], v2
	ds_read_b128 v[12:15], v2 offset:32
	ds_read_b128 v[8:11], v2 offset:64
	ds_read_b128 v[4:7], v2 offset:96
	v_xor_b32_e32 v2, 1, v202
	v_add_u32_e32 v86, 64, v86
	s_add_i32 s16, s31, s16
	v_cmp_lt_i32_e32 vcc, v2, v86
	s_ashr_i32 s17, s16, 31
	s_lshl_b64 s[16:17], s[16:17], 13
	v_cndmask_b32_e32 v2, v202, v2, vcc
	v_lshlrev_b32_e32 v86, 2, v2
	s_waitcnt lgkmcnt(3)
	v_mul_f32_e32 v66, v66, v82
	v_lshl_add_u64 v[16:17], v[158:159], 0, s[16:17]
	s_lshl_b32 s12, s30, 8
	s_nop 1
	v_mov_b32_dpp v87, v66 quad_perm:[1,0,3,2] row_mask:0xf bank_mask:0xf bound_ctrl:1
	v_lshl_add_u64 v[16:17], v[16:17], 0, s[12:13]
	v_lshlrev_b32_e32 v2, 1, v160
	s_waitcnt lgkmcnt(0)
	v_lshl_add_u64 v[16:17], v[16:17], 0, v[2:3]
	v_lshl_add_u64 v[16:17], v[16:17], 0, v[176:177]
	v_lshl_add_u64 v[16:17], v[16:17], 0, s[14:15]
	s_and_saveexec_b64 s[16:17], s[8:9]
	s_cbranch_execz .LBB0_530
	s_waitcnt lgkmcnt(0)
	v_cvt_pk_bf16_f32 v2, v66, v87
	global_store_dword v[16:17], v2, off
.LBB0_530:
	s_or_b64 exec, exec, s[16:17]
	v_mul_f32_e32 v2, v50, v82
	s_nop 1
	v_mov_b32_dpp v50, v2 quad_perm:[1,0,3,2] row_mask:0xf bank_mask:0xf bound_ctrl:1
	s_and_saveexec_b64 s[16:17], s[8:9]
	s_cbranch_execz .LBB0_532
	s_waitcnt lgkmcnt(0)
	v_cvt_pk_bf16_f32 v2, v2, v50
	global_store_dword v[16:17], v2, off offset:64
.LBB0_532:
	s_or_b64 exec, exec, s[16:17]
	v_mul_f32_e32 v2, v34, v82
	s_nop 1
	v_mov_b32_dpp v34, v2 quad_perm:[1,0,3,2] row_mask:0xf bank_mask:0xf bound_ctrl:1
	s_and_saveexec_b64 s[16:17], s[8:9]
	s_cbranch_execz .LBB0_534
	s_waitcnt lgkmcnt(0)
	v_cvt_pk_bf16_f32 v2, v2, v34
	global_store_dword v[16:17], v2, off offset:128
.LBB0_534:
	s_or_b64 exec, exec, s[16:17]
	v_mul_f32_e32 v2, v18, v82
	s_nop 1
	v_mov_b32_dpp v18, v2 quad_perm:[1,0,3,2] row_mask:0xf bank_mask:0xf bound_ctrl:1
	s_and_saveexec_b64 s[16:17], s[8:9]
	s_cbranch_execz .LBB0_536
	s_waitcnt lgkmcnt(0)
	v_cvt_pk_bf16_f32 v2, v2, v18
	global_store_dword v[16:17], v2, off offset:192
.LBB0_536:
	s_or_b64 exec, exec, s[16:17]
	v_mul_f32_e32 v2, v67, v83
	s_waitcnt lgkmcnt(0)
	s_nop 1
	v_mov_b32_dpp v18, v2 quad_perm:[1,0,3,2] row_mask:0xf bank_mask:0xf bound_ctrl:1
	s_and_saveexec_b64 s[16:17], s[8:9]
	s_cbranch_execz .LBB0_538
	v_add_co_u32_e32 v66, vcc, 0x2000, v16
	s_waitcnt lgkmcnt(0)
	v_cvt_pk_bf16_f32 v2, v2, v18
	s_nop 0
	v_addc_co_u32_e32 v67, vcc, 0, v17, vcc
	global_store_dword v[66:67], v2, off
.LBB0_538:
	s_or_b64 exec, exec, s[16:17]
	v_mul_f32_e32 v2, v51, v83
	s_waitcnt lgkmcnt(0)
	s_nop 1
	v_mov_b32_dpp v18, v2 quad_perm:[1,0,3,2] row_mask:0xf bank_mask:0xf bound_ctrl:1
	s_and_saveexec_b64 s[16:17], s[8:9]
	s_cbranch_execz .LBB0_540
	v_add_co_u32_e32 v50, vcc, 0x2000, v16
	s_waitcnt lgkmcnt(0)
	v_cvt_pk_bf16_f32 v2, v2, v18
	s_nop 0
	v_addc_co_u32_e32 v51, vcc, 0, v17, vcc
	global_store_dword v[50:51], v2, off offset:64
.LBB0_540:
	s_or_b64 exec, exec, s[16:17]
	v_mul_f32_e32 v2, v35, v83
	s_waitcnt lgkmcnt(0)
	s_nop 1
	v_mov_b32_dpp v18, v2 quad_perm:[1,0,3,2] row_mask:0xf bank_mask:0xf bound_ctrl:1
	s_and_saveexec_b64 s[16:17], s[8:9]
	s_cbranch_execz .LBB0_542
	v_add_co_u32_e32 v34, vcc, 0x2000, v16
	s_waitcnt lgkmcnt(0)
	v_cvt_pk_bf16_f32 v2, v2, v18
	s_nop 0
	v_addc_co_u32_e32 v35, vcc, 0, v17, vcc
	global_store_dword v[34:35], v2, off offset:128
.LBB0_542:
	s_or_b64 exec, exec, s[16:17]
	v_mul_f32_e32 v2, v19, v83
	s_waitcnt lgkmcnt(0)
	s_nop 1
	v_mov_b32_dpp v18, v2 quad_perm:[1,0,3,2] row_mask:0xf bank_mask:0xf bound_ctrl:1
	s_and_saveexec_b64 s[16:17], s[8:9]
	s_cbranch_execz .LBB0_544
	s_waitcnt lgkmcnt(0)
	v_cvt_pk_bf16_f32 v2, v2, v18
	v_add_co_u32_e32 v18, vcc, 0x2000, v16
	s_nop 1
	v_addc_co_u32_e32 v19, vcc, 0, v17, vcc
	global_store_dword v[18:19], v2, off offset:192
.LBB0_544:
	s_or_b64 exec, exec, s[16:17]
	v_mul_f32_e32 v2, v68, v84
	s_waitcnt lgkmcnt(0)
	s_nop 1
	v_mov_b32_dpp v18, v2 quad_perm:[1,0,3,2] row_mask:0xf bank_mask:0xf bound_ctrl:1
	s_and_saveexec_b64 s[16:17], s[8:9]
	s_cbranch_execz .LBB0_546
	s_waitcnt lgkmcnt(0)
	v_cvt_pk_bf16_f32 v2, v2, v18
	v_add_co_u32_e32 v18, vcc, 0x4000, v16
	s_nop 1
	v_addc_co_u32_e32 v19, vcc, 0, v17, vcc
	global_store_dword v[18:19], v2, off
.LBB0_546:
	s_or_b64 exec, exec, s[16:17]
	v_mul_f32_e32 v2, v52, v84
	s_waitcnt lgkmcnt(0)
	s_nop 1
	v_mov_b32_dpp v18, v2 quad_perm:[1,0,3,2] row_mask:0xf bank_mask:0xf bound_ctrl:1
	s_and_saveexec_b64 s[16:17], s[8:9]
	s_cbranch_execz .LBB0_548
	s_waitcnt lgkmcnt(0)
	v_cvt_pk_bf16_f32 v2, v2, v18
	v_add_co_u32_e32 v18, vcc, 0x4000, v16
	s_nop 1
	v_addc_co_u32_e32 v19, vcc, 0, v17, vcc
	global_store_dword v[18:19], v2, off offset:64
.LBB0_548:
	s_or_b64 exec, exec, s[16:17]
	v_mul_f32_e32 v2, v36, v84
	s_waitcnt lgkmcnt(0)
	s_nop 1
	v_mov_b32_dpp v18, v2 quad_perm:[1,0,3,2] row_mask:0xf bank_mask:0xf bound_ctrl:1
	s_and_saveexec_b64 s[16:17], s[8:9]
	s_cbranch_execz .LBB0_550
	s_waitcnt lgkmcnt(0)
	v_cvt_pk_bf16_f32 v2, v2, v18
	v_add_co_u32_e32 v18, vcc, 0x4000, v16
	s_nop 1
	v_addc_co_u32_e32 v19, vcc, 0, v17, vcc
	global_store_dword v[18:19], v2, off offset:128
.LBB0_550:
	s_or_b64 exec, exec, s[16:17]
	v_mul_f32_e32 v2, v20, v84
	s_waitcnt lgkmcnt(0)
	s_nop 1
	v_mov_b32_dpp v18, v2 quad_perm:[1,0,3,2] row_mask:0xf bank_mask:0xf bound_ctrl:1
	s_and_saveexec_b64 s[16:17], s[8:9]
	s_cbranch_execz .LBB0_552
	s_waitcnt lgkmcnt(0)
	v_cvt_pk_bf16_f32 v2, v2, v18
	v_add_co_u32_e32 v18, vcc, 0x4000, v16
	s_nop 1
	v_addc_co_u32_e32 v19, vcc, 0, v17, vcc
	global_store_dword v[18:19], v2, off offset:192
.LBB0_552:
	s_or_b64 exec, exec, s[16:17]
	v_mul_f32_e32 v2, v69, v85
	s_waitcnt lgkmcnt(0)
	s_nop 1
	v_mov_b32_dpp v18, v2 quad_perm:[1,0,3,2] row_mask:0xf bank_mask:0xf bound_ctrl:1
	s_and_saveexec_b64 s[16:17], s[8:9]
	s_cbranch_execz .LBB0_554
	s_waitcnt lgkmcnt(0)
	v_cvt_pk_bf16_f32 v2, v2, v18
	v_add_co_u32_e32 v18, vcc, 0x6000, v16
	s_nop 1
	v_addc_co_u32_e32 v19, vcc, 0, v17, vcc
	global_store_dword v[18:19], v2, off
.LBB0_554:
	s_or_b64 exec, exec, s[16:17]
	v_mul_f32_e32 v2, v53, v85
	s_waitcnt lgkmcnt(0)
	s_nop 1
	v_mov_b32_dpp v18, v2 quad_perm:[1,0,3,2] row_mask:0xf bank_mask:0xf bound_ctrl:1
	s_and_saveexec_b64 s[16:17], s[8:9]
	s_cbranch_execz .LBB0_556
	s_waitcnt lgkmcnt(0)
	v_cvt_pk_bf16_f32 v2, v2, v18
	v_add_co_u32_e32 v18, vcc, 0x6000, v16
	s_nop 1
	v_addc_co_u32_e32 v19, vcc, 0, v17, vcc
	global_store_dword v[18:19], v2, off offset:64
.LBB0_556:
	s_or_b64 exec, exec, s[16:17]
	v_mul_f32_e32 v2, v37, v85
	s_waitcnt lgkmcnt(0)
	s_nop 1
	v_mov_b32_dpp v18, v2 quad_perm:[1,0,3,2] row_mask:0xf bank_mask:0xf bound_ctrl:1
	s_and_saveexec_b64 s[16:17], s[8:9]
	s_cbranch_execz .LBB0_558
	s_waitcnt lgkmcnt(0)
	v_cvt_pk_bf16_f32 v2, v2, v18
	v_add_co_u32_e32 v18, vcc, 0x6000, v16
	s_nop 1
	v_addc_co_u32_e32 v19, vcc, 0, v17, vcc
	global_store_dword v[18:19], v2, off offset:128
.LBB0_558:
	s_or_b64 exec, exec, s[16:17]
	v_mul_f32_e32 v2, v21, v85
	s_waitcnt lgkmcnt(0)
	s_nop 1
	v_mov_b32_dpp v18, v2 quad_perm:[1,0,3,2] row_mask:0xf bank_mask:0xf bound_ctrl:1
	s_and_saveexec_b64 s[16:17], s[8:9]
	s_cbranch_execz .LBB0_560
	s_waitcnt lgkmcnt(0)
	v_cvt_pk_bf16_f32 v2, v2, v18
	v_add_co_u32_e32 v18, vcc, 0x6000, v16
	s_nop 1
	v_addc_co_u32_e32 v19, vcc, 0, v17, vcc
	global_store_dword v[18:19], v2, off offset:192
.LBB0_560:
	s_or_b64 exec, exec, s[16:17]
	v_mul_f32_e32 v2, v70, v12
	s_waitcnt lgkmcnt(0)
	s_nop 1
	v_mov_b32_dpp v18, v2 quad_perm:[1,0,3,2] row_mask:0xf bank_mask:0xf bound_ctrl:1
	s_and_saveexec_b64 s[16:17], s[8:9]
	s_cbranch_execz .LBB0_562
	s_waitcnt lgkmcnt(0)
	v_cvt_pk_bf16_f32 v2, v2, v18
	v_add_co_u32_e32 v18, vcc, 0x10000, v16
	s_nop 1
	v_addc_co_u32_e32 v19, vcc, 0, v17, vcc
	global_store_dword v[18:19], v2, off
.LBB0_562:
	s_or_b64 exec, exec, s[16:17]
	v_mul_f32_e32 v2, v54, v12
	s_waitcnt lgkmcnt(0)
	s_nop 1
	v_mov_b32_dpp v18, v2 quad_perm:[1,0,3,2] row_mask:0xf bank_mask:0xf bound_ctrl:1
	s_and_saveexec_b64 s[16:17], s[8:9]
	s_cbranch_execz .LBB0_564
	s_waitcnt lgkmcnt(0)
	v_cvt_pk_bf16_f32 v2, v2, v18
	v_add_co_u32_e32 v18, vcc, 0x10000, v16
	s_nop 1
	v_addc_co_u32_e32 v19, vcc, 0, v17, vcc
	global_store_dword v[18:19], v2, off offset:64
.LBB0_564:
	s_or_b64 exec, exec, s[16:17]
	v_mul_f32_e32 v2, v38, v12
	s_waitcnt lgkmcnt(0)
	s_nop 1
	v_mov_b32_dpp v18, v2 quad_perm:[1,0,3,2] row_mask:0xf bank_mask:0xf bound_ctrl:1
	s_and_saveexec_b64 s[16:17], s[8:9]
	s_cbranch_execz .LBB0_566
	s_waitcnt lgkmcnt(0)
	v_cvt_pk_bf16_f32 v2, v2, v18
	v_add_co_u32_e32 v18, vcc, 0x10000, v16
	s_nop 1
	v_addc_co_u32_e32 v19, vcc, 0, v17, vcc
	global_store_dword v[18:19], v2, off offset:128
.LBB0_566:
	s_or_b64 exec, exec, s[16:17]
	v_mul_f32_e32 v2, v22, v12
	s_nop 1
	v_mov_b32_dpp v12, v2 quad_perm:[1,0,3,2] row_mask:0xf bank_mask:0xf bound_ctrl:1
	s_and_saveexec_b64 s[16:17], s[8:9]
	s_cbranch_execz .LBB0_568
	s_waitcnt lgkmcnt(1)
	v_add_co_u32_e32 v18, vcc, 0x10000, v16
	s_waitcnt lgkmcnt(0)
	v_cvt_pk_bf16_f32 v2, v2, v12
	s_nop 0
	v_addc_co_u32_e32 v19, vcc, 0, v17, vcc
	global_store_dword v[18:19], v2, off offset:192
.LBB0_568:
	s_or_b64 exec, exec, s[16:17]
	v_mul_f32_e32 v2, v71, v13
	s_waitcnt lgkmcnt(0)
	s_nop 1
	v_mov_b32_dpp v12, v2 quad_perm:[1,0,3,2] row_mask:0xf bank_mask:0xf bound_ctrl:1
	s_and_saveexec_b64 s[16:17], s[8:9]
	s_cbranch_execz .LBB0_570
	v_add_co_u32_e32 v18, vcc, 0x12000, v16
	s_waitcnt lgkmcnt(0)
	v_cvt_pk_bf16_f32 v2, v2, v12
	s_nop 0
	v_addc_co_u32_e32 v19, vcc, 0, v17, vcc
	global_store_dword v[18:19], v2, off
.LBB0_570:
	s_or_b64 exec, exec, s[16:17]
	v_mul_f32_e32 v2, v55, v13
	s_waitcnt lgkmcnt(0)
	s_nop 1
	v_mov_b32_dpp v12, v2 quad_perm:[1,0,3,2] row_mask:0xf bank_mask:0xf bound_ctrl:1
	s_and_saveexec_b64 s[16:17], s[8:9]
	s_cbranch_execz .LBB0_572
	v_add_co_u32_e32 v18, vcc, 0x12000, v16
	s_waitcnt lgkmcnt(0)
	v_cvt_pk_bf16_f32 v2, v2, v12
	s_nop 0
	v_addc_co_u32_e32 v19, vcc, 0, v17, vcc
	global_store_dword v[18:19], v2, off offset:64
.LBB0_572:
	s_or_b64 exec, exec, s[16:17]
	v_mul_f32_e32 v2, v39, v13
	s_waitcnt lgkmcnt(0)
	s_nop 1
	v_mov_b32_dpp v12, v2 quad_perm:[1,0,3,2] row_mask:0xf bank_mask:0xf bound_ctrl:1
	s_and_saveexec_b64 s[16:17], s[8:9]
	s_cbranch_execz .LBB0_574
	v_add_co_u32_e32 v18, vcc, 0x12000, v16
	s_waitcnt lgkmcnt(0)
	v_cvt_pk_bf16_f32 v2, v2, v12
	s_nop 0
	v_addc_co_u32_e32 v19, vcc, 0, v17, vcc
	global_store_dword v[18:19], v2, off offset:128
.LBB0_574:
	s_or_b64 exec, exec, s[16:17]
	v_mul_f32_e32 v2, v23, v13
	s_waitcnt lgkmcnt(0)
	s_nop 1
	v_mov_b32_dpp v12, v2 quad_perm:[1,0,3,2] row_mask:0xf bank_mask:0xf bound_ctrl:1
	s_and_saveexec_b64 s[16:17], s[8:9]
	s_cbranch_execz .LBB0_576
	s_waitcnt lgkmcnt(0)
	v_cvt_pk_bf16_f32 v2, v2, v12
	v_add_co_u32_e32 v12, vcc, 0x12000, v16
	s_nop 1
	v_addc_co_u32_e32 v13, vcc, 0, v17, vcc
	global_store_dword v[12:13], v2, off offset:192
.LBB0_576:
	s_or_b64 exec, exec, s[16:17]
	v_mul_f32_e32 v2, v72, v14
	s_waitcnt lgkmcnt(0)
	s_nop 1
	v_mov_b32_dpp v12, v2 quad_perm:[1,0,3,2] row_mask:0xf bank_mask:0xf bound_ctrl:1
	s_and_saveexec_b64 s[16:17], s[8:9]
	s_cbranch_execz .LBB0_578
	s_waitcnt lgkmcnt(0)
	v_cvt_pk_bf16_f32 v2, v2, v12
	v_add_co_u32_e32 v12, vcc, 0x14000, v16
	s_nop 1
	v_addc_co_u32_e32 v13, vcc, 0, v17, vcc
	global_store_dword v[12:13], v2, off
.LBB0_578:
	s_or_b64 exec, exec, s[16:17]
	v_mul_f32_e32 v2, v56, v14
	s_waitcnt lgkmcnt(0)
	s_nop 1
	v_mov_b32_dpp v12, v2 quad_perm:[1,0,3,2] row_mask:0xf bank_mask:0xf bound_ctrl:1
	s_and_saveexec_b64 s[16:17], s[8:9]
	s_cbranch_execz .LBB0_580
	s_waitcnt lgkmcnt(0)
	v_cvt_pk_bf16_f32 v2, v2, v12
	v_add_co_u32_e32 v12, vcc, 0x14000, v16
	s_nop 1
	v_addc_co_u32_e32 v13, vcc, 0, v17, vcc
	global_store_dword v[12:13], v2, off offset:64
.LBB0_580:
	s_or_b64 exec, exec, s[16:17]
	v_mul_f32_e32 v2, v40, v14
	s_waitcnt lgkmcnt(0)
	s_nop 1
	v_mov_b32_dpp v12, v2 quad_perm:[1,0,3,2] row_mask:0xf bank_mask:0xf bound_ctrl:1
	s_and_saveexec_b64 s[16:17], s[8:9]
	s_cbranch_execz .LBB0_582
	s_waitcnt lgkmcnt(0)
	v_cvt_pk_bf16_f32 v2, v2, v12
	v_add_co_u32_e32 v12, vcc, 0x14000, v16
	s_nop 1
	v_addc_co_u32_e32 v13, vcc, 0, v17, vcc
	global_store_dword v[12:13], v2, off offset:128
.LBB0_582:
	s_or_b64 exec, exec, s[16:17]
	v_mul_f32_e32 v2, v24, v14
	s_waitcnt lgkmcnt(0)
	s_nop 1
	v_mov_b32_dpp v12, v2 quad_perm:[1,0,3,2] row_mask:0xf bank_mask:0xf bound_ctrl:1
	s_and_saveexec_b64 s[16:17], s[8:9]
	s_cbranch_execz .LBB0_584
	s_waitcnt lgkmcnt(0)
	v_cvt_pk_bf16_f32 v2, v2, v12
	v_add_co_u32_e32 v12, vcc, 0x14000, v16
	s_nop 1
	v_addc_co_u32_e32 v13, vcc, 0, v17, vcc
	global_store_dword v[12:13], v2, off offset:192
.LBB0_584:
	s_or_b64 exec, exec, s[16:17]
	v_mul_f32_e32 v2, v73, v15
	s_waitcnt lgkmcnt(0)
	s_nop 1
	v_mov_b32_dpp v12, v2 quad_perm:[1,0,3,2] row_mask:0xf bank_mask:0xf bound_ctrl:1
	s_and_saveexec_b64 s[16:17], s[8:9]
	s_cbranch_execz .LBB0_586
	s_waitcnt lgkmcnt(0)
	v_cvt_pk_bf16_f32 v2, v2, v12
	v_add_co_u32_e32 v12, vcc, 0x16000, v16
	s_nop 1
	v_addc_co_u32_e32 v13, vcc, 0, v17, vcc
	global_store_dword v[12:13], v2, off
.LBB0_586:
	s_or_b64 exec, exec, s[16:17]
	v_mul_f32_e32 v2, v57, v15
	s_waitcnt lgkmcnt(0)
	s_nop 1
	v_mov_b32_dpp v12, v2 quad_perm:[1,0,3,2] row_mask:0xf bank_mask:0xf bound_ctrl:1
	s_and_saveexec_b64 s[16:17], s[8:9]
	s_cbranch_execz .LBB0_588
	s_waitcnt lgkmcnt(0)
	v_cvt_pk_bf16_f32 v2, v2, v12
	v_add_co_u32_e32 v12, vcc, 0x16000, v16
	s_nop 1
	v_addc_co_u32_e32 v13, vcc, 0, v17, vcc
	global_store_dword v[12:13], v2, off offset:64
.LBB0_588:
	s_or_b64 exec, exec, s[16:17]
	v_mul_f32_e32 v2, v41, v15
	s_waitcnt lgkmcnt(0)
	s_nop 1
	v_mov_b32_dpp v12, v2 quad_perm:[1,0,3,2] row_mask:0xf bank_mask:0xf bound_ctrl:1
	s_and_saveexec_b64 s[16:17], s[8:9]
	s_cbranch_execz .LBB0_590
	s_waitcnt lgkmcnt(0)
	v_cvt_pk_bf16_f32 v2, v2, v12
	v_add_co_u32_e32 v12, vcc, 0x16000, v16
	s_nop 1
	v_addc_co_u32_e32 v13, vcc, 0, v17, vcc
	global_store_dword v[12:13], v2, off offset:128
.LBB0_590:
	s_or_b64 exec, exec, s[16:17]
	v_mul_f32_e32 v2, v25, v15
	s_waitcnt lgkmcnt(0)
	s_nop 1
	v_mov_b32_dpp v12, v2 quad_perm:[1,0,3,2] row_mask:0xf bank_mask:0xf bound_ctrl:1
	s_and_saveexec_b64 s[16:17], s[8:9]
	s_cbranch_execz .LBB0_592
	s_waitcnt lgkmcnt(0)
	v_cvt_pk_bf16_f32 v2, v2, v12
	v_add_co_u32_e32 v12, vcc, 0x16000, v16
	s_nop 1
	v_addc_co_u32_e32 v13, vcc, 0, v17, vcc
	global_store_dword v[12:13], v2, off offset:192
.LBB0_592:
	s_or_b64 exec, exec, s[16:17]
	v_mul_f32_e32 v2, v74, v8
	s_waitcnt lgkmcnt(0)
	s_nop 1
	v_mov_b32_dpp v12, v2 quad_perm:[1,0,3,2] row_mask:0xf bank_mask:0xf bound_ctrl:1
	s_and_saveexec_b64 s[16:17], s[8:9]
	s_cbranch_execz .LBB0_594
	s_waitcnt lgkmcnt(0)
	v_cvt_pk_bf16_f32 v2, v2, v12
	v_add_co_u32_e32 v12, vcc, 0x20000, v16
	s_nop 1
	v_addc_co_u32_e32 v13, vcc, 0, v17, vcc
	global_store_dword v[12:13], v2, off
.LBB0_594:
	s_or_b64 exec, exec, s[16:17]
	v_mul_f32_e32 v2, v58, v8
	s_waitcnt lgkmcnt(0)
	s_nop 1
	v_mov_b32_dpp v12, v2 quad_perm:[1,0,3,2] row_mask:0xf bank_mask:0xf bound_ctrl:1
	s_and_saveexec_b64 s[16:17], s[8:9]
	s_cbranch_execz .LBB0_596
	s_waitcnt lgkmcnt(0)
	v_cvt_pk_bf16_f32 v2, v2, v12
	v_add_co_u32_e32 v12, vcc, 0x20000, v16
	s_nop 1
	v_addc_co_u32_e32 v13, vcc, 0, v17, vcc
	global_store_dword v[12:13], v2, off offset:64
.LBB0_596:
	s_or_b64 exec, exec, s[16:17]
	v_mul_f32_e32 v2, v42, v8
	s_waitcnt lgkmcnt(0)
	s_nop 1
	v_mov_b32_dpp v12, v2 quad_perm:[1,0,3,2] row_mask:0xf bank_mask:0xf bound_ctrl:1
	s_and_saveexec_b64 s[16:17], s[8:9]
	s_cbranch_execz .LBB0_598
	s_waitcnt lgkmcnt(0)
	v_cvt_pk_bf16_f32 v2, v2, v12
	v_add_co_u32_e32 v12, vcc, 0x20000, v16
	s_nop 1
	v_addc_co_u32_e32 v13, vcc, 0, v17, vcc
	global_store_dword v[12:13], v2, off offset:128
.LBB0_598:
	s_or_b64 exec, exec, s[16:17]
	v_mul_f32_e32 v2, v26, v8
	s_nop 1
	v_mov_b32_dpp v8, v2 quad_perm:[1,0,3,2] row_mask:0xf bank_mask:0xf bound_ctrl:1
	s_and_saveexec_b64 s[16:17], s[8:9]
	s_cbranch_execz .LBB0_600
	s_waitcnt lgkmcnt(1)
	v_add_co_u32_e32 v12, vcc, 0x20000, v16
	s_waitcnt lgkmcnt(0)
	v_cvt_pk_bf16_f32 v2, v2, v8
	s_nop 0
	v_addc_co_u32_e32 v13, vcc, 0, v17, vcc
	global_store_dword v[12:13], v2, off offset:192
.LBB0_600:
	s_or_b64 exec, exec, s[16:17]
	v_mul_f32_e32 v2, v75, v9
	s_waitcnt lgkmcnt(0)
	s_nop 1
	v_mov_b32_dpp v8, v2 quad_perm:[1,0,3,2] row_mask:0xf bank_mask:0xf bound_ctrl:1
	s_and_saveexec_b64 s[16:17], s[8:9]
	s_cbranch_execz .LBB0_602
	v_add_co_u32_e32 v12, vcc, 0x22000, v16
	s_waitcnt lgkmcnt(0)
	v_cvt_pk_bf16_f32 v2, v2, v8
	s_nop 0
	v_addc_co_u32_e32 v13, vcc, 0, v17, vcc
	global_store_dword v[12:13], v2, off
.LBB0_602:
	s_or_b64 exec, exec, s[16:17]
	v_mul_f32_e32 v2, v59, v9
	s_waitcnt lgkmcnt(0)
	s_nop 1
	v_mov_b32_dpp v8, v2 quad_perm:[1,0,3,2] row_mask:0xf bank_mask:0xf bound_ctrl:1
	s_and_saveexec_b64 s[16:17], s[8:9]
	s_cbranch_execz .LBB0_604
	v_add_co_u32_e32 v12, vcc, 0x22000, v16
	s_waitcnt lgkmcnt(0)
	v_cvt_pk_bf16_f32 v2, v2, v8
	s_nop 0
	v_addc_co_u32_e32 v13, vcc, 0, v17, vcc
	global_store_dword v[12:13], v2, off offset:64
.LBB0_604:
	s_or_b64 exec, exec, s[16:17]
	v_mul_f32_e32 v2, v43, v9
	s_waitcnt lgkmcnt(0)
	s_nop 1
	v_mov_b32_dpp v8, v2 quad_perm:[1,0,3,2] row_mask:0xf bank_mask:0xf bound_ctrl:1
	s_and_saveexec_b64 s[16:17], s[8:9]
	s_cbranch_execz .LBB0_606
	v_add_co_u32_e32 v12, vcc, 0x22000, v16
	s_waitcnt lgkmcnt(0)
	v_cvt_pk_bf16_f32 v2, v2, v8
	s_nop 0
	v_addc_co_u32_e32 v13, vcc, 0, v17, vcc
	global_store_dword v[12:13], v2, off offset:128
.LBB0_606:
	s_or_b64 exec, exec, s[16:17]
	v_mul_f32_e32 v2, v27, v9
	s_waitcnt lgkmcnt(0)
	s_nop 1
	v_mov_b32_dpp v8, v2 quad_perm:[1,0,3,2] row_mask:0xf bank_mask:0xf bound_ctrl:1
	s_and_saveexec_b64 s[16:17], s[8:9]
	s_cbranch_execz .LBB0_608
	s_waitcnt lgkmcnt(0)
	v_cvt_pk_bf16_f32 v2, v2, v8
	v_add_co_u32_e32 v8, vcc, 0x22000, v16
	s_nop 1
	v_addc_co_u32_e32 v9, vcc, 0, v17, vcc
	global_store_dword v[8:9], v2, off offset:192
.LBB0_608:
	s_or_b64 exec, exec, s[16:17]
	v_mul_f32_e32 v2, v76, v10
	s_waitcnt lgkmcnt(0)
	s_nop 1
	v_mov_b32_dpp v8, v2 quad_perm:[1,0,3,2] row_mask:0xf bank_mask:0xf bound_ctrl:1
	s_and_saveexec_b64 s[16:17], s[8:9]
	s_cbranch_execz .LBB0_610
	s_waitcnt lgkmcnt(0)
	v_cvt_pk_bf16_f32 v2, v2, v8
	v_add_co_u32_e32 v8, vcc, 0x24000, v16
	s_nop 1
	v_addc_co_u32_e32 v9, vcc, 0, v17, vcc
	global_store_dword v[8:9], v2, off
.LBB0_610:
	s_or_b64 exec, exec, s[16:17]
	v_mul_f32_e32 v2, v60, v10
	s_waitcnt lgkmcnt(0)
	s_nop 1
	v_mov_b32_dpp v8, v2 quad_perm:[1,0,3,2] row_mask:0xf bank_mask:0xf bound_ctrl:1
	s_and_saveexec_b64 s[16:17], s[8:9]
	s_cbranch_execz .LBB0_612
	s_waitcnt lgkmcnt(0)
	v_cvt_pk_bf16_f32 v2, v2, v8
	v_add_co_u32_e32 v8, vcc, 0x24000, v16
	s_nop 1
	v_addc_co_u32_e32 v9, vcc, 0, v17, vcc
	global_store_dword v[8:9], v2, off offset:64
.LBB0_612:
	s_or_b64 exec, exec, s[16:17]
	v_mul_f32_e32 v2, v44, v10
	s_waitcnt lgkmcnt(0)
	s_nop 1
	v_mov_b32_dpp v8, v2 quad_perm:[1,0,3,2] row_mask:0xf bank_mask:0xf bound_ctrl:1
	s_and_saveexec_b64 s[16:17], s[8:9]
	s_cbranch_execz .LBB0_614
	s_waitcnt lgkmcnt(0)
	v_cvt_pk_bf16_f32 v2, v2, v8
	v_add_co_u32_e32 v8, vcc, 0x24000, v16
	s_nop 1
	v_addc_co_u32_e32 v9, vcc, 0, v17, vcc
	global_store_dword v[8:9], v2, off offset:128
.LBB0_614:
	s_or_b64 exec, exec, s[16:17]
	v_mul_f32_e32 v2, v28, v10
	s_waitcnt lgkmcnt(0)
	s_nop 1
	v_mov_b32_dpp v8, v2 quad_perm:[1,0,3,2] row_mask:0xf bank_mask:0xf bound_ctrl:1
	s_and_saveexec_b64 s[16:17], s[8:9]
	s_cbranch_execz .LBB0_616
	s_waitcnt lgkmcnt(0)
	v_cvt_pk_bf16_f32 v2, v2, v8
	v_add_co_u32_e32 v8, vcc, 0x24000, v16
	s_nop 1
	v_addc_co_u32_e32 v9, vcc, 0, v17, vcc
	global_store_dword v[8:9], v2, off offset:192
.LBB0_616:
	s_or_b64 exec, exec, s[16:17]
	v_mul_f32_e32 v2, v77, v11
	s_waitcnt lgkmcnt(0)
	s_nop 1
	v_mov_b32_dpp v8, v2 quad_perm:[1,0,3,2] row_mask:0xf bank_mask:0xf bound_ctrl:1
	s_and_saveexec_b64 s[16:17], s[8:9]
	s_cbranch_execz .LBB0_618
	s_waitcnt lgkmcnt(0)
	v_cvt_pk_bf16_f32 v2, v2, v8
	v_add_co_u32_e32 v8, vcc, 0x26000, v16
	s_nop 1
	v_addc_co_u32_e32 v9, vcc, 0, v17, vcc
	global_store_dword v[8:9], v2, off
.LBB0_618:
	s_or_b64 exec, exec, s[16:17]
	v_mul_f32_e32 v2, v61, v11
	s_waitcnt lgkmcnt(0)
	s_nop 1
	v_mov_b32_dpp v8, v2 quad_perm:[1,0,3,2] row_mask:0xf bank_mask:0xf bound_ctrl:1
	s_and_saveexec_b64 s[16:17], s[8:9]
	s_cbranch_execz .LBB0_620
	s_waitcnt lgkmcnt(0)
	v_cvt_pk_bf16_f32 v2, v2, v8
	v_add_co_u32_e32 v8, vcc, 0x26000, v16
	s_nop 1
	v_addc_co_u32_e32 v9, vcc, 0, v17, vcc
	global_store_dword v[8:9], v2, off offset:64
.LBB0_620:
	s_or_b64 exec, exec, s[16:17]
	v_mul_f32_e32 v2, v45, v11
	s_waitcnt lgkmcnt(0)
	s_nop 1
	v_mov_b32_dpp v8, v2 quad_perm:[1,0,3,2] row_mask:0xf bank_mask:0xf bound_ctrl:1
	s_and_saveexec_b64 s[16:17], s[8:9]
	s_cbranch_execz .LBB0_622
	s_waitcnt lgkmcnt(0)
	v_cvt_pk_bf16_f32 v2, v2, v8
	v_add_co_u32_e32 v8, vcc, 0x26000, v16
	s_nop 1
	v_addc_co_u32_e32 v9, vcc, 0, v17, vcc
	global_store_dword v[8:9], v2, off offset:128
.LBB0_622:
	s_or_b64 exec, exec, s[16:17]
	v_mul_f32_e32 v2, v29, v11
	s_waitcnt lgkmcnt(0)
	s_nop 1
	v_mov_b32_dpp v8, v2 quad_perm:[1,0,3,2] row_mask:0xf bank_mask:0xf bound_ctrl:1
	s_and_saveexec_b64 s[16:17], s[8:9]
	s_cbranch_execz .LBB0_624
	s_waitcnt lgkmcnt(0)
	v_cvt_pk_bf16_f32 v2, v2, v8
	v_add_co_u32_e32 v8, vcc, 0x26000, v16
	s_nop 1
	v_addc_co_u32_e32 v9, vcc, 0, v17, vcc
	global_store_dword v[8:9], v2, off offset:192
.LBB0_624:
	s_or_b64 exec, exec, s[16:17]
	v_mul_f32_e32 v2, v78, v4
	s_waitcnt lgkmcnt(0)
	s_nop 1
	v_mov_b32_dpp v8, v2 quad_perm:[1,0,3,2] row_mask:0xf bank_mask:0xf bound_ctrl:1
	s_and_saveexec_b64 s[16:17], s[8:9]
	s_cbranch_execz .LBB0_626
	s_waitcnt lgkmcnt(0)
	v_cvt_pk_bf16_f32 v2, v2, v8
	v_add_co_u32_e32 v8, vcc, 0x30000, v16
	s_nop 1
	v_addc_co_u32_e32 v9, vcc, 0, v17, vcc
	global_store_dword v[8:9], v2, off
.LBB0_626:
	s_or_b64 exec, exec, s[16:17]
	v_mul_f32_e32 v2, v62, v4
	s_waitcnt lgkmcnt(0)
	s_nop 1
	v_mov_b32_dpp v8, v2 quad_perm:[1,0,3,2] row_mask:0xf bank_mask:0xf bound_ctrl:1
	s_and_saveexec_b64 s[16:17], s[8:9]
	s_cbranch_execz .LBB0_628
	s_waitcnt lgkmcnt(0)
	v_cvt_pk_bf16_f32 v2, v2, v8
	v_add_co_u32_e32 v8, vcc, 0x30000, v16
	s_nop 1
	v_addc_co_u32_e32 v9, vcc, 0, v17, vcc
	global_store_dword v[8:9], v2, off offset:64
.LBB0_628:
	s_or_b64 exec, exec, s[16:17]
	v_mul_f32_e32 v2, v46, v4
	s_waitcnt lgkmcnt(0)
	s_nop 1
	v_mov_b32_dpp v8, v2 quad_perm:[1,0,3,2] row_mask:0xf bank_mask:0xf bound_ctrl:1
	s_and_saveexec_b64 s[16:17], s[8:9]
	s_cbranch_execz .LBB0_630
	s_waitcnt lgkmcnt(0)
	v_cvt_pk_bf16_f32 v2, v2, v8
	v_add_co_u32_e32 v8, vcc, 0x30000, v16
	s_nop 1
	v_addc_co_u32_e32 v9, vcc, 0, v17, vcc
	global_store_dword v[8:9], v2, off offset:128
.LBB0_630:
	s_or_b64 exec, exec, s[16:17]
	v_mul_f32_e32 v2, v30, v4
	s_nop 1
	v_mov_b32_dpp v4, v2 quad_perm:[1,0,3,2] row_mask:0xf bank_mask:0xf bound_ctrl:1
	s_and_saveexec_b64 s[16:17], s[8:9]
	s_cbranch_execz .LBB0_632
	s_waitcnt lgkmcnt(1)
	v_add_co_u32_e32 v8, vcc, 0x30000, v16
	s_waitcnt lgkmcnt(0)
	v_cvt_pk_bf16_f32 v2, v2, v4
	s_nop 0
	v_addc_co_u32_e32 v9, vcc, 0, v17, vcc
	global_store_dword v[8:9], v2, off offset:192
.LBB0_632:
	s_or_b64 exec, exec, s[16:17]
	v_mul_f32_e32 v2, v79, v5
	s_waitcnt lgkmcnt(0)
	s_nop 1
	v_mov_b32_dpp v4, v2 quad_perm:[1,0,3,2] row_mask:0xf bank_mask:0xf bound_ctrl:1
	s_and_saveexec_b64 s[16:17], s[8:9]
	s_cbranch_execz .LBB0_634
	v_add_co_u32_e32 v8, vcc, 0x32000, v16
	s_waitcnt lgkmcnt(0)
	v_cvt_pk_bf16_f32 v2, v2, v4
	s_nop 0
	v_addc_co_u32_e32 v9, vcc, 0, v17, vcc
	global_store_dword v[8:9], v2, off
.LBB0_634:
	s_or_b64 exec, exec, s[16:17]
	v_mul_f32_e32 v2, v63, v5
	s_waitcnt lgkmcnt(0)
	s_nop 1
	v_mov_b32_dpp v4, v2 quad_perm:[1,0,3,2] row_mask:0xf bank_mask:0xf bound_ctrl:1
	s_and_saveexec_b64 s[16:17], s[8:9]
	s_cbranch_execz .LBB0_636
	v_add_co_u32_e32 v8, vcc, 0x32000, v16
	s_waitcnt lgkmcnt(0)
	v_cvt_pk_bf16_f32 v2, v2, v4
	s_nop 0
	v_addc_co_u32_e32 v9, vcc, 0, v17, vcc
	global_store_dword v[8:9], v2, off offset:64
.LBB0_636:
	s_or_b64 exec, exec, s[16:17]
	v_mul_f32_e32 v2, v47, v5
	s_waitcnt lgkmcnt(0)
	s_nop 1
	v_mov_b32_dpp v4, v2 quad_perm:[1,0,3,2] row_mask:0xf bank_mask:0xf bound_ctrl:1
	s_and_saveexec_b64 s[16:17], s[8:9]
	s_cbranch_execz .LBB0_638
	v_add_co_u32_e32 v8, vcc, 0x32000, v16
	s_waitcnt lgkmcnt(0)
	v_cvt_pk_bf16_f32 v2, v2, v4
	s_nop 0
	v_addc_co_u32_e32 v9, vcc, 0, v17, vcc
	global_store_dword v[8:9], v2, off offset:128
.LBB0_638:
	s_or_b64 exec, exec, s[16:17]
	v_mul_f32_e32 v2, v31, v5
	s_waitcnt lgkmcnt(0)
	s_nop 1
	v_mov_b32_dpp v4, v2 quad_perm:[1,0,3,2] row_mask:0xf bank_mask:0xf bound_ctrl:1
	s_and_saveexec_b64 s[16:17], s[8:9]
	s_cbranch_execz .LBB0_640
	s_waitcnt lgkmcnt(0)
	v_cvt_pk_bf16_f32 v2, v2, v4
	v_add_co_u32_e32 v4, vcc, 0x32000, v16
	s_nop 1
	v_addc_co_u32_e32 v5, vcc, 0, v17, vcc
	global_store_dword v[4:5], v2, off offset:192
.LBB0_640:
	s_or_b64 exec, exec, s[16:17]
	v_mul_f32_e32 v2, v80, v6
	s_waitcnt lgkmcnt(0)
	s_nop 1
	v_mov_b32_dpp v4, v2 quad_perm:[1,0,3,2] row_mask:0xf bank_mask:0xf bound_ctrl:1
	s_and_saveexec_b64 s[16:17], s[8:9]
	s_cbranch_execz .LBB0_642
	s_waitcnt lgkmcnt(0)
	v_cvt_pk_bf16_f32 v2, v2, v4
	v_add_co_u32_e32 v4, vcc, 0x34000, v16
	s_nop 1
	v_addc_co_u32_e32 v5, vcc, 0, v17, vcc
	global_store_dword v[4:5], v2, off
.LBB0_642:
	s_or_b64 exec, exec, s[16:17]
	v_mul_f32_e32 v2, v64, v6
	s_waitcnt lgkmcnt(0)
	s_nop 1
	v_mov_b32_dpp v4, v2 quad_perm:[1,0,3,2] row_mask:0xf bank_mask:0xf bound_ctrl:1
	s_and_saveexec_b64 s[16:17], s[8:9]
	s_cbranch_execz .LBB0_644
	s_waitcnt lgkmcnt(0)
	v_cvt_pk_bf16_f32 v2, v2, v4
	v_add_co_u32_e32 v4, vcc, 0x34000, v16
	s_nop 1
	v_addc_co_u32_e32 v5, vcc, 0, v17, vcc
	global_store_dword v[4:5], v2, off offset:64
.LBB0_644:
	s_or_b64 exec, exec, s[16:17]
	v_mul_f32_e32 v2, v48, v6
	s_waitcnt lgkmcnt(0)
	s_nop 1
	v_mov_b32_dpp v4, v2 quad_perm:[1,0,3,2] row_mask:0xf bank_mask:0xf bound_ctrl:1
	s_and_saveexec_b64 s[16:17], s[8:9]
	s_cbranch_execz .LBB0_646
	s_waitcnt lgkmcnt(0)
	v_cvt_pk_bf16_f32 v2, v2, v4
	v_add_co_u32_e32 v4, vcc, 0x34000, v16
	s_nop 1
	v_addc_co_u32_e32 v5, vcc, 0, v17, vcc
	global_store_dword v[4:5], v2, off offset:128
.LBB0_646:
	s_or_b64 exec, exec, s[16:17]
	v_mul_f32_e32 v2, v32, v6
	s_waitcnt lgkmcnt(0)
	s_nop 1
	v_mov_b32_dpp v4, v2 quad_perm:[1,0,3,2] row_mask:0xf bank_mask:0xf bound_ctrl:1
	s_and_saveexec_b64 s[16:17], s[8:9]
	s_cbranch_execz .LBB0_648
	s_waitcnt lgkmcnt(0)
	v_cvt_pk_bf16_f32 v2, v2, v4
	v_add_co_u32_e32 v4, vcc, 0x34000, v16
	s_nop 1
	v_addc_co_u32_e32 v5, vcc, 0, v17, vcc
	global_store_dword v[4:5], v2, off offset:192
.LBB0_648:
	s_or_b64 exec, exec, s[16:17]
	v_mul_f32_e32 v2, v81, v7
	s_waitcnt lgkmcnt(0)
	s_nop 1
	v_mov_b32_dpp v4, v2 quad_perm:[1,0,3,2] row_mask:0xf bank_mask:0xf bound_ctrl:1
	s_and_saveexec_b64 s[16:17], s[8:9]
	s_cbranch_execz .LBB0_650
	s_waitcnt lgkmcnt(0)
	v_cvt_pk_bf16_f32 v2, v2, v4
	v_add_co_u32_e32 v4, vcc, 0x36000, v16
	s_nop 1
	v_addc_co_u32_e32 v5, vcc, 0, v17, vcc
	global_store_dword v[4:5], v2, off
.LBB0_650:
	s_or_b64 exec, exec, s[16:17]
	v_mul_f32_e32 v2, v65, v7
	s_waitcnt lgkmcnt(0)
	s_nop 1
	v_mov_b32_dpp v4, v2 quad_perm:[1,0,3,2] row_mask:0xf bank_mask:0xf bound_ctrl:1
	s_and_saveexec_b64 s[16:17], s[8:9]
	s_cbranch_execz .LBB0_652
	s_waitcnt lgkmcnt(0)
	v_cvt_pk_bf16_f32 v2, v2, v4
	v_add_co_u32_e32 v4, vcc, 0x36000, v16
	s_nop 1
	v_addc_co_u32_e32 v5, vcc, 0, v17, vcc
	global_store_dword v[4:5], v2, off offset:64
.LBB0_652:
	s_or_b64 exec, exec, s[16:17]
	v_mul_f32_e32 v2, v49, v7
	s_waitcnt lgkmcnt(0)
	s_nop 1
	v_mov_b32_dpp v4, v2 quad_perm:[1,0,3,2] row_mask:0xf bank_mask:0xf bound_ctrl:1
	s_and_saveexec_b64 s[16:17], s[8:9]
	s_cbranch_execz .LBB0_654
	s_waitcnt lgkmcnt(0)
	v_cvt_pk_bf16_f32 v2, v2, v4
	v_add_co_u32_e32 v4, vcc, 0x36000, v16
	s_nop 1
	v_addc_co_u32_e32 v5, vcc, 0, v17, vcc
	global_store_dword v[4:5], v2, off offset:128
.LBB0_654:
	s_or_b64 exec, exec, s[16:17]
	v_mul_f32_e32 v2, v33, v7
	s_waitcnt lgkmcnt(0)
	s_nop 1
	v_mov_b32_dpp v4, v2 quad_perm:[1,0,3,2] row_mask:0xf bank_mask:0xf bound_ctrl:1
	s_and_saveexec_b64 s[16:17], s[8:9]
	s_cbranch_execz .LBB0_495
	s_waitcnt lgkmcnt(0)
	v_cvt_pk_bf16_f32 v2, v2, v4
	v_add_co_u32_e32 v4, vcc, 0x36000, v16
	s_nop 1
	v_addc_co_u32_e32 v5, vcc, 0, v17, vcc
	global_store_dword v[4:5], v2, off offset:192
	s_branch .LBB0_495
